# tile assignment variant weighting retention steps 1.3x (diff 14/10,15/7,13/6,12/4,11/3,9/2,8/1,5/0)
# baseline (speedup 1.0000x reference)
; __device__ __forceinline__ int lane_id() { return (int)__builtin_amdgcn_mbcnt_hi(~0u, __builtin_amdgcn_mbcnt_lo(~0u, 0u)); }
; __global__ void __launch_bounds__(NWAVES * 64, 2) fwd(Args args) {
;     ...
;         unsigned char* wsp = ws; asm volatile("" : "+s"(wsp)); const unsigned char* tbl = wsp + WS_PTRS;
;         const float* ret_gn = ld_uptr(tbl, 4); const float* diff_qn = ld_uptr(tbl, 5); const float* diff_kn = ld_uptr(tbl, 6); const float* lq1 = ld_uptr(tbl, 7); const float* lk1 = ld_uptr(tbl, 8);
;         const float* lq2 = ld_uptr(tbl, 9); const float* lk2 = ld_uptr(tbl, 10); const float* subln = ld_uptr(tbl, 11);
;         bf16_t* Z = (bf16_t*)(wsp + WS_Z); bf16_t* MIX = (bf16_t*)(wsp + WS_MIX);
;         int lane2 = lane_id(); asm volatile("" : "+v"(lane2));
;         const float d1 = wave_sum(lq1[lane2] * lk1[lane2]), d2 = wave_sum(lq2[lane2] * lk2[lane2]);
;         float lam; { float lv = __expf(d1) - __expf(d2) + 0.2f; asm volatile("" : "+v"(lv)); lam = __uint_as_float(__builtin_amdgcn_readfirstlane(__float_as_uint(lv))); }
;         const float mq = wave_max(fabsf(diff_qn[lane2])), mk = wave_max(fabsf(diff_kn[lane2]));
;         float shift; { float sv = 11.541560327111707f * mq * mk; asm volatile("" : "+v"(sv)); shift = __uint_as_float(__builtin_amdgcn_readfirstlane(__float_as_uint(sv))); }
;         for (int pi = vcu; pi < 256; pi += G) {
.LBB0_561:
	s_cmp_lt_i32 s82, 3
	s_cselect_b64 s[2:3], -1, 0
	v_writelane_b32 v254, s2, 2
	s_and_b64 s[0:1], s[2:3], s[0:1]
	s_andn2_b64 vcc, exec, s[0:1]
	v_writelane_b32 v254, s3, 3
	s_cbranch_vccnz .LBB0_654
	v_writelane_b32 v254, s96, 4
	v_mov_b32_e32 v181, 0
	v_mbcnt_lo_u32_b32 v13, -1, 0
	v_writelane_b32 v254, s97, 5
	v_writelane_b32 v254, s94, 6
	v_writelane_b32 v254, s93, 7
	v_writelane_b32 v254, s92, 8
	v_writelane_b32 v254, s90, 9
	v_mbcnt_hi_u32_b32 v183, -1, v13
	v_mov_b32_e32 v12, 0x20000
	v_writelane_b32 v254, s91, 10
	v_writelane_b32 v254, s87, 11
	v_writelane_b32 v254, s88, 12
	v_mov_b32_e32 v16, v183
	s_mov_b32 s27, 0
	v_writelane_b32 v254, s89, 13
	v_writelane_b32 v254, s86, 14
	v_writelane_b32 v254, s84, 15
	s_nop 1
	v_writelane_b32 v254, s85, 16
	v_writelane_b32 v254, s79, 17
	v_writelane_b32 v254, s77, 18
	v_writelane_b32 v254, s80, 19
	s_mov_b64 s[0:1], s[80:81]
	s_add_u32 s2, s0, 0x20020
	s_addc_u32 s3, s1, 0
	global_load_dwordx4 v[0:3], v181, s[2:3] offset:16
	global_load_dwordx4 v[4:7], v181, s[2:3] offset:32
	global_load_dwordx4 v[8:11], v181, s[2:3] offset:48
	v_writelane_b32 v254, s81, 20
	global_load_dwordx4 v[12:15], v12, s[0:1] offset:32
	v_writelane_b32 v254, s82, 21
	v_ashrrev_i32_e32 v17, 31, v16
	v_lshlrev_b64 v[16:17], 2, v[16:17]
	v_writelane_b32 v254, s83, 22
	s_cmpk_gt_i32 s95, 0xff
	s_waitcnt vmcnt(0)
	v_readfirstlane_b32 s3, v3
	v_readfirstlane_b32 s2, v2
	v_readfirstlane_b32 s5, v5
	v_readfirstlane_b32 s4, v4
	v_readfirstlane_b32 s7, v7
	v_readfirstlane_b32 s6, v6
	v_readfirstlane_b32 s9, v9
	v_readfirstlane_b32 s8, v8
	v_lshl_add_u64 v[2:3], s[2:3], 0, v[16:17]
	v_lshl_add_u64 v[4:5], s[4:5], 0, v[16:17]
	v_lshl_add_u64 v[6:7], s[6:7], 0, v[16:17]
	v_lshl_add_u64 v[8:9], s[8:9], 0, v[16:17]
	flat_load_dword v18, v[2:3]
	flat_load_dword v19, v[4:5]
	flat_load_dword v20, v[6:7]
	flat_load_dword v21, v[8:9]
	v_and_b32_e32 v2, 64, v183
	v_xor_b32_e32 v3, 1, v183
	v_add_u32_e32 v2, 64, v2
	v_cmp_lt_i32_e32 vcc, v3, v2
	v_xor_b32_e32 v4, 2, v183
	v_xor_b32_e32 v5, 4, v183
	v_cndmask_b32_e32 v3, v183, v3, vcc
	v_lshlrev_b32_e32 v9, 2, v3
	v_cmp_lt_i32_e32 vcc, v4, v2
	v_xor_b32_e32 v6, 8, v183
	v_xor_b32_e32 v7, 16, v183
	v_cndmask_b32_e32 v4, v183, v4, vcc
	v_lshlrev_b32_e32 v4, 2, v4
	v_cmp_lt_i32_e32 vcc, v5, v2
	v_xor_b32_e32 v8, 32, v183
	v_readfirstlane_b32 s5, v1
	v_cndmask_b32_e32 v5, v183, v5, vcc
	v_lshlrev_b32_e32 v5, 2, v5
	v_cmp_lt_i32_e32 vcc, v6, v2
	v_readfirstlane_b32 s3, v15
	v_readfirstlane_b32 s2, v14
	v_cndmask_b32_e32 v6, v183, v6, vcc
	v_lshlrev_b32_e32 v6, 2, v6
	v_cmp_lt_i32_e32 vcc, v7, v2
	v_readfirstlane_b32 s4, v0
	v_readfirstlane_b32 s85, v11
	v_cndmask_b32_e32 v7, v183, v7, vcc
	v_lshlrev_b32_e32 v7, 2, v7
	v_cmp_lt_i32_e32 vcc, v8, v2
	v_readfirstlane_b32 s84, v10
	s_waitcnt vmcnt(0) lgkmcnt(0)
	v_mul_f32_e32 v3, v18, v19
	ds_bpermute_b32 v3, v9, v3
	v_mul_f32_e32 v22, v20, v21
	ds_bpermute_b32 v22, v9, v22
	v_cndmask_b32_e32 v2, v183, v8, vcc
	v_lshlrev_b32_e32 v8, 2, v2
	s_waitcnt lgkmcnt(1)
	v_fmac_f32_e32 v3, v18, v19
	ds_bpermute_b32 v18, v4, v3
	s_waitcnt lgkmcnt(1)
	v_fmac_f32_e32 v22, v20, v21
	ds_bpermute_b32 v19, v4, v22
	s_waitcnt lgkmcnt(1)
	v_add_f32_e32 v3, v3, v18
	s_waitcnt lgkmcnt(0)
	v_add_f32_e32 v18, v22, v19
	ds_bpermute_b32 v19, v5, v3
	ds_bpermute_b32 v20, v5, v18
	s_waitcnt lgkmcnt(1)
	v_add_f32_e32 v3, v3, v19
	s_waitcnt lgkmcnt(0)
	v_add_f32_e32 v18, v18, v20
	ds_bpermute_b32 v19, v6, v3
	ds_bpermute_b32 v20, v6, v18
	s_waitcnt lgkmcnt(1)
	v_add_f32_e32 v3, v3, v19
	s_waitcnt lgkmcnt(0)
	v_add_f32_e32 v18, v18, v20
	ds_bpermute_b32 v19, v7, v3
	ds_bpermute_b32 v20, v7, v18
	s_waitcnt lgkmcnt(1)
	v_add_f32_e32 v2, v3, v19
	s_waitcnt lgkmcnt(0)
	v_add_f32_e32 v3, v18, v20
	ds_bpermute_b32 v18, v8, v2
	ds_bpermute_b32 v19, v8, v3
	s_waitcnt lgkmcnt(1)
	v_add_f32_e32 v1, v2, v18
	s_waitcnt lgkmcnt(0)
	v_add_f32_e32 v2, v3, v19
	v_mul_f32_e32 v1, 0x3fb8aa3b, v1
	v_mul_f32_e32 v2, 0x3fb8aa3b, v2
	v_exp_f32_e32 v14, v1
	v_exp_f32_e32 v15, v2
	v_lshl_add_u64 v[0:1], s[2:3], 0, v[16:17]
	v_lshl_add_u64 v[2:3], s[4:5], 0, v[16:17]
	v_readfirstlane_b32 s2, v13
	v_sub_f32_e32 v14, v14, v15
	v_add_f32_e32 v14, 0x3e4ccccd, v14
	flat_load_dword v15, v[0:1]
	flat_load_dword v16, v[2:3]
	v_writelane_b32 v254, s2, 23
	v_readfirstlane_b32 s2, v12
	v_readfirstlane_b32 s28, v14
	s_waitcnt vmcnt(0) lgkmcnt(0)
	v_and_b32_e32 v0, 0x7fffffff, v15
	v_and_b32_e32 v1, 0x7fffffff, v16
	ds_bpermute_b32 v0, v9, v0
	ds_bpermute_b32 v1, v9, v1
	v_max_f32_e64 v2, |v15|, |v15|
	v_max_f32_e64 v3, |v16|, |v16|
	v_writelane_b32 v254, s2, 24
	s_waitcnt lgkmcnt(1)
	v_max_f32_e32 v0, v0, v0
	s_waitcnt lgkmcnt(0)
	v_max_f32_e32 v1, v1, v1
	v_max_f32_e32 v0, v2, v0
	v_max_f32_e32 v1, v3, v1
	ds_bpermute_b32 v2, v4, v0
	ds_bpermute_b32 v3, v4, v1
	s_waitcnt lgkmcnt(1)
	v_max_f32_e32 v2, v2, v2
	s_waitcnt lgkmcnt(0)
	v_max_f32_e32 v3, v3, v3
	v_max_f32_e32 v0, v0, v2
	v_max_f32_e32 v1, v1, v3
	ds_bpermute_b32 v2, v5, v0
	ds_bpermute_b32 v3, v5, v1
	s_waitcnt lgkmcnt(1)
	v_max_f32_e32 v2, v2, v2
	s_waitcnt lgkmcnt(0)
	v_max_f32_e32 v3, v3, v3
	v_max_f32_e32 v0, v0, v2
	v_max_f32_e32 v1, v1, v3
	ds_bpermute_b32 v2, v6, v0
	ds_bpermute_b32 v3, v6, v1
	s_waitcnt lgkmcnt(1)
	v_max_f32_e32 v2, v2, v2
	s_waitcnt lgkmcnt(0)
	v_max_f32_e32 v3, v3, v3
	v_max_f32_e32 v0, v0, v2
	v_max_f32_e32 v1, v1, v3
	ds_bpermute_b32 v2, v7, v0
	ds_bpermute_b32 v3, v7, v1
	s_waitcnt lgkmcnt(1)
	v_max_f32_e32 v2, v2, v2
	s_waitcnt lgkmcnt(0)
	v_max_f32_e32 v3, v3, v3
	v_max_f32_e32 v0, v0, v2
	v_max_f32_e32 v1, v1, v3
	ds_bpermute_b32 v2, v8, v0
	ds_bpermute_b32 v3, v8, v1
	s_waitcnt lgkmcnt(1)
	v_max_f32_e32 v2, v2, v2
	s_waitcnt lgkmcnt(0)
	v_max_f32_e32 v3, v3, v3
	v_max_f32_e32 v0, v0, v2
	v_max_f32_e32 v1, v1, v3
	v_mul_f32_e32 v0, 0x4138aa3b, v0
	v_mul_f32_e32 v0, v0, v1
	s_nop 0
	v_readfirstlane_b32 s2, v0
	s_cbranch_scc1 .LBB0_653
; __global__ void __launch_bounds__(NWAVES * 64, 2) fwd(Args args) {
;     ...
;         for (int pi = vcu; pi < 256; pi += G) {
;             const int bh = pi >> 3, tp = pi & 7, b = bh >> 3, h = bh & 7;
;             attn_item<true>(lds, Z, MIX, b, h, 15 - tp, lam, shift, subln, 0, wid, 0);
;             ret_pair(lds, Z, MIX, b, h, 15 - tp, tp, ret_gn + 128 * h, wid);
;             attn_item<true>(lds, Z, MIX, b, h, tp, lam, shift, subln, 0, wid, 0);
;         }
	s_add_u32 s30, s0, 0x5300000
	s_addc_u32 s31, s1, 0
	s_add_u32 s88, s0, 0x2f00000
	s_addc_u32 s89, s1, 0
	s_lshl_b32 s29, s60, 4
	s_lshl_b32 s34, s60, 3
	s_lshl_b32 s35, s60, 2
	s_add_i32 s90, s33, 0
	v_sub_f32_e64 v0, 0, s2
	s_add_u32 s2, s0, 0x54c2800
	v_writelane_b32 v254, s2, 25
	s_addc_u32 s2, s1, 0
	v_writelane_b32 v254, s2, 26
	s_lshl_b32 s2, s95, 5
	s_lshl_b32 s3, s78, 5
	v_writelane_b32 v254, s3, 27
	s_add_u32 s3, s0, 0x54c0800
	v_writelane_b32 v254, s3, 28
	s_addc_u32 s3, s1, 0
	v_writelane_b32 v254, s3, 29
	s_add_u32 s0, s0, 0x54c0400
	v_writelane_b32 v254, s0, 30
	s_addc_u32 s0, s1, 0
	v_writelane_b32 v254, s0, 31
	v_writelane_b32 v254, s78, 32
	v_writelane_b32 v254, s66, 33
	v_writelane_b32 v254, s84, 34
	s_add_i32 s17, s90, 0x2000
	s_add_i32 s38, s90, 0x6000
	v_writelane_b32 v254, s85, 35
	v_writelane_b32 v254, s28, 36
	v_writelane_b32 v254, s30, 37
	s_add_i32 s39, s90, 0x8000
	s_add_i32 s18, s90, 0xa000
	v_writelane_b32 v254, s31, 38
	v_writelane_b32 v254, s88, 39
	s_add_i32 s40, s90, 0xc000
	s_add_i32 s41, s90, 0xe000
	v_writelane_b32 v254, s89, 40
	v_writelane_b32 v254, s29, 41
	v_writelane_b32 v254, s34, 42
	v_writelane_b32 v254, s35, 43
	v_writelane_b32 v254, s17, 44
	v_writelane_b32 v254, s38, 45
	v_writelane_b32 v254, s39, 46
	v_writelane_b32 v254, s18, 47
	v_writelane_b32 v254, s40, 48
	s_add_i32 s43, s90, 0x4000
	v_writelane_b32 v254, s41, 49
	v_mov_b32_e32 v1, v0
	v_mov_b32_e32 v2, v0
	v_mov_b32_e32 v3, v0
	s_movk_i32 s36, 0x3800
	s_mov_b64 s[14:15], 0x1800
	s_movk_i32 s16, 0x1000
	s_movk_i32 s37, 0x1c00
	s_mov_b64 s[96:97], 0x80
	s_movk_i32 s67, 0xe0
	s_movk_i32 s73, 0x60
	s_movk_i32 s74, 0x80
	s_movk_i32 s75, 0xa0
	s_movk_i32 s79, 0xc0
	s_mov_b64 s[92:93], 0x3000
	s_mov_b32 s42, 0x800000
	v_mov_b32_e32 v186, 0xe0
	s_mov_b32 s44, s95
	s_mov_b32 s101, 0
	s_mov_b32 s98, 0
	s_mov_b32 s99, 0x589bcdfe
	v_writelane_b32 v254, s43, 50
	s_branch .LBB0_565
.Lp2_item_done:
	v_readlane_b32 s17, v254, 44
	v_readlane_b32 s38, v254, 45
	v_readlane_b32 s39, v254, 46
	v_readlane_b32 s18, v254, 47
	v_readlane_b32 s40, v254, 48
	v_readlane_b32 s41, v254, 49
	v_readlane_b32 s43, v254, 50
	v_readlane_b32 s28, v254, 36
	v_readlane_b32 s30, v254, 37
	v_readlane_b32 s31, v254, 38
	v_readlane_b32 s88, v254, 39
	v_readlane_b32 s89, v254, 40
	v_readlane_b32 s29, v254, 41
	v_readlane_b32 s34, v254, 42
	v_readlane_b32 s35, v254, 43
	v_readlane_b32 s66, v254, 33
	v_readlane_b32 s84, v254, 34
	v_readlane_b32 s85, v254, 35
	v_readlane_b32 s78, v254, 32
	s_mov_b32 s27, 0
	s_movk_i32 s36, 0x3800
	s_mov_b64 s[14:15], 0x1800
	s_movk_i32 s16, 0x1000
	s_movk_i32 s37, 0x1c00
	s_mov_b64 s[96:97], 0x80
	s_movk_i32 s67, 0xe0
	s_movk_i32 s73, 0x60
	s_movk_i32 s74, 0x80
	s_movk_i32 s75, 0xa0
	s_movk_i32 s79, 0xc0
	s_mov_b64 s[92:93], 0x3000
	s_mov_b32 s42, 0x800000
	v_readlane_b32 s2, v254, 51
	v_readlane_b32 s0, v254, 27
	s_mov_b32 s98, 0
	s_mov_b32 s99, 0x589bcdfe
	s_add_i32 s95, s95, s78
	s_add_i32 s2, s2, s0
	s_add_i32 s44, s44, s78
	s_cmpk_gt_i32 s95, 0xff
	s_cbranch_scc1 .LBB0_653

; __device__ __forceinline__ int lane_id() { return (int)__builtin_amdgcn_mbcnt_hi(~0u, __builtin_amdgcn_mbcnt_lo(~0u, 0u)); }
; __device__ __forceinline__ void ret_pair(LAS unsigned char* lds, const bf16_t* Z, bf16_t* MIX, int b, int h, int tA, int tB, const float* gain, int wid) {
;     ...
;     int lf = lane_id(); asm volatile("" : "+v"(lf)); const int q16f = lf & 15, quadf = (lf >> 4) & 3;
; #pragma unroll
;     for (int which = 0; which < 2; ++which) {
;         f32x4 (&O)[8] = which ? OB : OA;
;         float ss = 0.f;
; #pragma unroll
;         for (int eb = 0; eb < 8; ++eb)
; #pragma unroll
;             for (int i = 0; i < 4; ++i) ss += O[eb][i] * O[eb][i];
;         ss = quad_sum(ss);
;         const float r = rsqrtf(ss * (1.0f / 128.0f) + EPS);
;         const int row = (which ? rowB0 : rowA0) + q16f;
;         const bf16_t* gp = Z + (size_t)row * DIN + gcol + 4 * quadf;
;         bf16_t* op = MIX + (size_t)row * DM + 128 * h + 4 * quadf;
.LBB0_640:
	s_lshl_b32 s0, s80, 2
	v_readlane_b32 s1, v254, 24
	s_add_u32 s0, s1, s0
	v_readlane_b32 s1, v254, 23
	v_readlane_b32 s2, v255, 3
	s_waitcnt lgkmcnt(0)
	v_mov_b32_e32 v4, v183
	s_addc_u32 s1, s1, 0
	s_add_i32 s4, s2, 1
	s_add_u32 s2, s30, s86
	v_and_b32_e32 v93, 15, v4
	v_lshrrev_b32_e32 v4, 2, v4
	s_addc_u32 s3, s31, 0
	v_and_b32_e32 v4, 12, v4
	v_lshlrev_b32_e32 v180, 1, v4
	v_lshlrev_b32_e32 v4, 2, v4
	v_mov_b32_e32 v5, v181
	v_or_b32_e32 v32, s5, v93
	v_mov_b64_e32 v[6:7], s[2:3]
	v_lshl_add_u64 v[4:5], s[0:1], 0, v[4:5]
	v_readlane_b32 s3, v255, 7
	s_mov_b64 s[6:7], 0x1000
	v_mad_i64_i32 v[8:9], vcc, v32, s36, v[6:7]
	v_mov_b32_e32 v29, v181
	v_or_b32_e32 v30, s3, v93
	v_lshl_add_u64 v[10:11], v[8:9], 0, v[180:181]
	v_mad_i64_i32 v[6:7], vcc, v30, s36, v[6:7]
	v_lshl_add_u64 v[10:11], v[10:11], 0, s[6:7]
	v_lshl_add_u64 v[6:7], v[6:7], 0, v[180:181]
	s_add_u32 s0, s88, s86
	s_addc_u32 s1, s89, 0
	v_lshl_add_u64 v[6:7], v[6:7], 0, s[6:7]
	global_load_dwordx4 v[96:99], v[4:5], off
	global_load_dwordx2 v[134:135], v[10:11], off
	global_load_dwordx2 v[150:151], v[6:7], off
	global_load_dwordx4 v[100:103], v[4:5], off offset:64
	global_load_dwordx2 v[136:137], v[10:11], off offset:32
	global_load_dwordx2 v[152:153], v[6:7], off offset:32
	global_load_dwordx4 v[104:107], v[4:5], off offset:128
	global_load_dwordx2 v[138:139], v[10:11], off offset:64
	global_load_dwordx2 v[154:155], v[6:7], off offset:64
	global_load_dwordx4 v[108:111], v[4:5], off offset:192
	global_load_dwordx2 v[140:141], v[10:11], off offset:96
	global_load_dwordx2 v[156:157], v[6:7], off offset:96
	global_load_dwordx4 v[112:115], v[4:5], off offset:256
	global_load_dwordx2 v[142:143], v[10:11], off offset:128
	global_load_dwordx2 v[158:159], v[6:7], off offset:128
	global_load_dwordx4 v[116:119], v[4:5], off offset:320
	global_load_dwordx2 v[144:145], v[10:11], off offset:160
	global_load_dwordx2 v[160:161], v[6:7], off offset:160
	global_load_dwordx4 v[120:123], v[4:5], off offset:384
	global_load_dwordx2 v[146:147], v[10:11], off offset:192
	global_load_dwordx2 v[162:163], v[6:7], off offset:192
	global_load_dwordx4 v[124:127], v[4:5], off offset:448
	global_load_dwordx2 v[148:149], v[10:11], off offset:224
	global_load_dwordx2 v[164:165], v[6:7], off offset:224
	v_lshl_add_u64 v[8:9], s[0:1], 0, v[180:181]
	v_mov_b32_e32 v28, v32
	v_mov_b32_e32 v31, v181
	v_lshlrev_b64 v[28:29], 12, v[28:29]
	v_lshlrev_b64 v[30:31], 12, v[30:31]
	v_lshl_add_u64 v[166:167], v[8:9], 0, v[28:29]
	v_lshl_add_u64 v[168:169], v[8:9], 0, v[30:31]
	v_mul_f32_e32 v33, v81, v81
	v_fmac_f32_e32 v33, v80, v80
	v_fmac_f32_e32 v33, v82, v82
	v_fmac_f32_e32 v33, v83, v83
	v_fmac_f32_e32 v33, v76, v76
	v_fmac_f32_e32 v33, v77, v77
	v_fmac_f32_e32 v33, v78, v78
	v_fmac_f32_e32 v33, v79, v79
	v_fmac_f32_e32 v33, v72, v72
	v_fmac_f32_e32 v33, v73, v73
	v_fmac_f32_e32 v33, v74, v74
	v_fmac_f32_e32 v33, v75, v75
	v_fmac_f32_e32 v33, v68, v68
	v_fmac_f32_e32 v33, v69, v69
	v_fmac_f32_e32 v33, v70, v70
	v_fmac_f32_e32 v33, v71, v71
	v_fmac_f32_e32 v33, v64, v64
	v_fmac_f32_e32 v33, v65, v65
	v_fmac_f32_e32 v33, v66, v66
	v_fmac_f32_e32 v33, v67, v67
	v_fmac_f32_e32 v33, v60, v60
	v_fmac_f32_e32 v33, v61, v61
	v_fmac_f32_e32 v33, v62, v62
	v_fmac_f32_e32 v33, v63, v63
	v_pk_mul_f32 v[84:85], v[56:57], v[56:57]
	v_pk_mul_f32 v[8:9], v[58:59], v[58:59]
	v_add_f32_e32 v33, v84, v33
	v_add_f32_e32 v33, v85, v33
	v_add_f32_e32 v8, v8, v33
	v_add_f32_e32 v33, v9, v8
	v_pk_mul_f32 v[84:85], v[52:53], v[52:53]
	v_pk_mul_f32 v[8:9], v[54:55], v[54:55]
	v_add_f32_e32 v33, v84, v33
	v_add_f32_e32 v33, v85, v33
	v_add_f32_e32 v8, v8, v33
	v_add_f32_e32 v33, v9, v8
	ds_swizzle_b32 v84, v33 offset:swizzle(SWAP,16)
	v_pk_mul_f32 v[90:91], v[16:17], v[16:17]
	v_pk_mul_f32 v[88:89], v[18:19], v[18:19]
	s_waitcnt lgkmcnt(0)
	v_add_f32_e32 v85, v33, v84
	v_mul_f32_e32 v84, v49, v49
	v_fmac_f32_e32 v84, v48, v48
	v_fmac_f32_e32 v84, v50, v50
	v_fmac_f32_e32 v84, v51, v51
	v_fmac_f32_e32 v84, v44, v44
	v_fmac_f32_e32 v84, v45, v45
	v_fmac_f32_e32 v84, v46, v46
	v_fmac_f32_e32 v84, v47, v47
	v_fmac_f32_e32 v84, v40, v40
	v_fmac_f32_e32 v84, v41, v41
	v_fmac_f32_e32 v84, v42, v42
	v_fmac_f32_e32 v84, v43, v43
	v_fmac_f32_e32 v84, v36, v36
	v_fmac_f32_e32 v84, v37, v37
	v_fmac_f32_e32 v84, v38, v38
	v_fmac_f32_e32 v84, v39, v39
	v_fmac_f32_e32 v84, v24, v24
	v_fmac_f32_e32 v84, v25, v25
	v_fmac_f32_e32 v84, v26, v26
	v_fmac_f32_e32 v84, v27, v27
	v_fmac_f32_e32 v84, v20, v20
	v_fmac_f32_e32 v84, v21, v21
	v_fmac_f32_e32 v84, v22, v22
	v_fmac_f32_e32 v84, v23, v23
	v_add_f32_e32 v84, v90, v84
	v_add_f32_e32 v84, v91, v84
	v_add_f32_e32 v84, v88, v84
	v_add_f32_e32 v84, v89, v84
	v_pk_mul_f32 v[90:91], v[12:13], v[12:13]
	v_pk_mul_f32 v[88:89], v[14:15], v[14:15]
	v_add_f32_e32 v84, v90, v84
	v_add_f32_e32 v84, v91, v84
	v_add_f32_e32 v84, v88, v84
	v_add_f32_e32 v84, v89, v84
	ds_swizzle_b32 v86, v84 offset:swizzle(SWAP,16)
	v_mov_b32_e32 v87, v85
	s_nop 1
	v_permlane32_swap_b32_e32 v85, v87
	s_waitcnt lgkmcnt(0)
	v_add_f32_e32 v84, v84, v86
	v_mov_b32_e32 v86, v84
	s_nop 1
	v_permlane32_swap_b32_e32 v84, v86
	v_pk_add_f32 v[84:85], v[84:85], v[86:87]
	s_brev_b32 s0, 60
	v_mov_b32_e32 v34, 0x358637bd
	v_pk_fma_f32 v[84:85], v[84:85], s[0:1], v[34:35] op_sel_hi:[1,0,0]
	s_mov_b32 s2, 0x800000
	v_mul_f32_e32 v34, 0x4b800000, v85
	v_cmp_gt_f32_e32 vcc, s2, v85
	v_mul_f32_e32 v35, 0x4b800000, v84
	v_cmp_gt_f32_e64 s[0:1], s2, v84
	v_cndmask_b32_e32 v34, v85, v34, vcc
	v_rsq_f32_e32 v85, v34
	v_cndmask_b32_e64 v35, v84, v35, s[0:1]
	v_rsq_f32_e32 v84, v35
	v_mul_f32_e32 v92, 0x45800000, v85
	v_cndmask_b32_e32 v92, v85, v92, vcc
	v_mul_f32_e32 v94, 0x45800000, v84
	v_cndmask_b32_e64 v94, v84, v94, s[0:1]
	s_mov_b32 s87, s27
	s_mov_b32 m0, s90
	s_mov_b32 s42, 0x800000
	s_mov_b32 s5, 0
	s_waitcnt vmcnt(0)
; __device__ __forceinline__ unsigned cvtpk(float lo, float hi) { f32x2 v = {lo, hi}; bf16x2_t b = __builtin_convertvector(v, bf16x2_t); return __builtin_bit_cast(unsigned, b); }
; __device__ __forceinline__ float bflo(unsigned u) { return __uint_as_float(u << 16); }
; __device__ __forceinline__ float bfhi(unsigned u) { return __uint_as_float(u & 0xffff0000u); }
; __device__ __forceinline__ void ret_pair(LAS unsigned char* lds, const bf16_t* Z, bf16_t* MIX, int b, int h, int tA, int tB, const float* gain, int wid) {
;     ...
; #pragma unroll
;         for (int eb = 0; eb < 8; ++eb) {
;             const u32x2 gw = *(const u32x2*)(gp + 16 * eb);
;             const f32x4 gn = *(const f32x4*)(gain + 16 * eb + 4 * quadf);
;             u32x2 w; w.x = cvtpk(O[eb][0] * r * gn.x * bflo(gw.x), O[eb][1] * r * gn.y * bfhi(gw.x));
;             w.y = cvtpk(O[eb][2] * r * gn.z * bflo(gw.y), O[eb][3] * r * gn.w * bfhi(gw.y));
;             *(u32x2*)(op + 16 * eb) = w;
;         }
	v_pk_mul_f32 v[80:81], v[80:81], v[92:93] op_sel_hi:[1,0]
	v_pk_mul_f32 v[82:83], v[82:83], v[92:93] op_sel_hi:[1,0]
	v_lshlrev_b32_e32 v28, 16, v134
	v_and_b32_e32 v29, 0xffff0000, v134
	v_lshlrev_b32_e32 v30, 16, v135
	v_and_b32_e32 v31, 0xffff0000, v135
	v_pk_mul_f32 v[80:81], v[96:97], v[80:81]
	v_pk_mul_f32 v[82:83], v[98:99], v[82:83]
	v_pk_mul_f32 v[80:81], v[80:81], v[28:29]
	v_pk_mul_f32 v[82:83], v[82:83], v[30:31]
	v_cvt_pk_bf16_f32 v80, v80, v81
	v_cvt_pk_bf16_f32 v81, v82, v83
	global_store_dwordx2 v[166:167], v[80:81], off
	v_pk_mul_f32 v[48:49], v[48:49], v[94:95] op_sel_hi:[1,0]
	v_pk_mul_f32 v[50:51], v[50:51], v[94:95] op_sel_hi:[1,0]
	v_lshlrev_b32_e32 v170, 16, v150
	v_and_b32_e32 v171, 0xffff0000, v150
	v_lshlrev_b32_e32 v172, 16, v151
	v_and_b32_e32 v173, 0xffff0000, v151
	v_pk_mul_f32 v[48:49], v[96:97], v[48:49]
	v_pk_mul_f32 v[50:51], v[98:99], v[50:51]
	v_pk_mul_f32 v[48:49], v[48:49], v[170:171]
	v_pk_mul_f32 v[50:51], v[50:51], v[172:173]
	v_cvt_pk_bf16_f32 v48, v48, v49
	v_cvt_pk_bf16_f32 v49, v50, v51
	global_store_dwordx2 v[168:169], v[48:49], off
	v_pk_mul_f32 v[76:77], v[76:77], v[92:93] op_sel_hi:[1,0]
	v_pk_mul_f32 v[78:79], v[78:79], v[92:93] op_sel_hi:[1,0]
	v_lshlrev_b32_e32 v28, 16, v136
	v_and_b32_e32 v29, 0xffff0000, v136
	v_lshlrev_b32_e32 v30, 16, v137
	v_and_b32_e32 v31, 0xffff0000, v137
	v_pk_mul_f32 v[76:77], v[100:101], v[76:77]
	v_pk_mul_f32 v[78:79], v[102:103], v[78:79]
	v_pk_mul_f32 v[76:77], v[76:77], v[28:29]
	v_pk_mul_f32 v[78:79], v[78:79], v[30:31]
	v_cvt_pk_bf16_f32 v76, v76, v77
	v_cvt_pk_bf16_f32 v77, v78, v79
	global_store_dwordx2 v[166:167], v[76:77], off offset:32
	v_pk_mul_f32 v[44:45], v[44:45], v[94:95] op_sel_hi:[1,0]
	v_pk_mul_f32 v[46:47], v[46:47], v[94:95] op_sel_hi:[1,0]
	v_lshlrev_b32_e32 v170, 16, v152
	v_and_b32_e32 v171, 0xffff0000, v152
	v_lshlrev_b32_e32 v172, 16, v153
	v_and_b32_e32 v173, 0xffff0000, v153
	v_pk_mul_f32 v[44:45], v[100:101], v[44:45]
	v_pk_mul_f32 v[46:47], v[102:103], v[46:47]
	v_pk_mul_f32 v[44:45], v[44:45], v[170:171]
	v_pk_mul_f32 v[46:47], v[46:47], v[172:173]
	v_cvt_pk_bf16_f32 v44, v44, v45
	v_cvt_pk_bf16_f32 v45, v46, v47
	global_store_dwordx2 v[168:169], v[44:45], off offset:32
	v_pk_mul_f32 v[72:73], v[72:73], v[92:93] op_sel_hi:[1,0]
	v_pk_mul_f32 v[74:75], v[74:75], v[92:93] op_sel_hi:[1,0]
	v_lshlrev_b32_e32 v28, 16, v138
	v_and_b32_e32 v29, 0xffff0000, v138
	v_lshlrev_b32_e32 v30, 16, v139
	v_and_b32_e32 v31, 0xffff0000, v139
	v_pk_mul_f32 v[72:73], v[104:105], v[72:73]
	v_pk_mul_f32 v[74:75], v[106:107], v[74:75]
	v_pk_mul_f32 v[72:73], v[72:73], v[28:29]
	v_pk_mul_f32 v[74:75], v[74:75], v[30:31]
	v_cvt_pk_bf16_f32 v72, v72, v73
	v_cvt_pk_bf16_f32 v73, v74, v75
	global_store_dwordx2 v[166:167], v[72:73], off offset:64
	v_pk_mul_f32 v[40:41], v[40:41], v[94:95] op_sel_hi:[1,0]
	v_pk_mul_f32 v[42:43], v[42:43], v[94:95] op_sel_hi:[1,0]
	v_lshlrev_b32_e32 v170, 16, v154
	v_and_b32_e32 v171, 0xffff0000, v154
	v_lshlrev_b32_e32 v172, 16, v155
	v_and_b32_e32 v173, 0xffff0000, v155
	v_pk_mul_f32 v[40:41], v[104:105], v[40:41]
	v_pk_mul_f32 v[42:43], v[106:107], v[42:43]
	v_pk_mul_f32 v[40:41], v[40:41], v[170:171]
	v_pk_mul_f32 v[42:43], v[42:43], v[172:173]
	v_cvt_pk_bf16_f32 v40, v40, v41
	v_cvt_pk_bf16_f32 v41, v42, v43
	global_store_dwordx2 v[168:169], v[40:41], off offset:64
	v_pk_mul_f32 v[68:69], v[68:69], v[92:93] op_sel_hi:[1,0]
	v_pk_mul_f32 v[70:71], v[70:71], v[92:93] op_sel_hi:[1,0]
	v_lshlrev_b32_e32 v28, 16, v140
	v_and_b32_e32 v29, 0xffff0000, v140
	v_lshlrev_b32_e32 v30, 16, v141
	v_and_b32_e32 v31, 0xffff0000, v141
	v_pk_mul_f32 v[68:69], v[108:109], v[68:69]
	v_pk_mul_f32 v[70:71], v[110:111], v[70:71]
	v_pk_mul_f32 v[68:69], v[68:69], v[28:29]
	v_pk_mul_f32 v[70:71], v[70:71], v[30:31]
	v_cvt_pk_bf16_f32 v68, v68, v69
	v_cvt_pk_bf16_f32 v69, v70, v71
	global_store_dwordx2 v[166:167], v[68:69], off offset:96
	v_pk_mul_f32 v[36:37], v[36:37], v[94:95] op_sel_hi:[1,0]
	v_pk_mul_f32 v[38:39], v[38:39], v[94:95] op_sel_hi:[1,0]
	v_lshlrev_b32_e32 v170, 16, v156
	v_and_b32_e32 v171, 0xffff0000, v156
	v_lshlrev_b32_e32 v172, 16, v157
	v_and_b32_e32 v173, 0xffff0000, v157
	v_pk_mul_f32 v[36:37], v[108:109], v[36:37]
	v_pk_mul_f32 v[38:39], v[110:111], v[38:39]
	v_pk_mul_f32 v[36:37], v[36:37], v[170:171]
	v_pk_mul_f32 v[38:39], v[38:39], v[172:173]
	v_cvt_pk_bf16_f32 v36, v36, v37
	v_cvt_pk_bf16_f32 v37, v38, v39
	global_store_dwordx2 v[168:169], v[36:37], off offset:96
	v_pk_mul_f32 v[64:65], v[64:65], v[92:93] op_sel_hi:[1,0]
	v_pk_mul_f32 v[66:67], v[66:67], v[92:93] op_sel_hi:[1,0]
	v_lshlrev_b32_e32 v28, 16, v142
	v_and_b32_e32 v29, 0xffff0000, v142
	v_lshlrev_b32_e32 v30, 16, v143
	v_and_b32_e32 v31, 0xffff0000, v143
	v_pk_mul_f32 v[64:65], v[112:113], v[64:65]
	v_pk_mul_f32 v[66:67], v[114:115], v[66:67]
	v_pk_mul_f32 v[64:65], v[64:65], v[28:29]
	v_pk_mul_f32 v[66:67], v[66:67], v[30:31]
	v_cvt_pk_bf16_f32 v64, v64, v65
	v_cvt_pk_bf16_f32 v65, v66, v67
; __device__ __forceinline__ unsigned cvtpk(float lo, float hi) { f32x2 v = {lo, hi}; bf16x2_t b = __builtin_convertvector(v, bf16x2_t); return __builtin_bit_cast(unsigned, b); }
; __device__ __forceinline__ float bflo(unsigned u) { return __uint_as_float(u << 16); }
; __device__ __forceinline__ float bfhi(unsigned u) { return __uint_as_float(u & 0xffff0000u); }
; __device__ __forceinline__ void ret_pair(LAS unsigned char* lds, const bf16_t* Z, bf16_t* MIX, int b, int h, int tA, int tB, const float* gain, int wid) {
;     ...
; #pragma unroll
;         for (int eb = 0; eb < 8; ++eb) {
;             const u32x2 gw = *(const u32x2*)(gp + 16 * eb);
;             const f32x4 gn = *(const f32x4*)(gain + 16 * eb + 4 * quadf);
;             u32x2 w; w.x = cvtpk(O[eb][0] * r * gn.x * bflo(gw.x), O[eb][1] * r * gn.y * bfhi(gw.x));
;             w.y = cvtpk(O[eb][2] * r * gn.z * bflo(gw.y), O[eb][3] * r * gn.w * bfhi(gw.y));
;             *(u32x2*)(op + 16 * eb) = w;
;         }
;     }
; __global__ void __launch_bounds__(NWAVES * 64, 2) fwd(Args args) {
;     ...
;         for (int pi = vcu; pi < 256; pi += G) {
;             const int bh = pi >> 3, tp = pi & 7, b = bh >> 3, h = bh & 7;
;             attn_item<true>(lds, Z, MIX, b, h, 15 - tp, lam, shift, subln, 0, wid, 0);
;             ret_pair(lds, Z, MIX, b, h, 15 - tp, tp, ret_gn + 128 * h, wid);
;             attn_item<true>(lds, Z, MIX, b, h, tp, lam, shift, subln, 0, wid, 0);
	global_store_dwordx2 v[166:167], v[64:65], off offset:128
	v_pk_mul_f32 v[24:25], v[24:25], v[94:95] op_sel_hi:[1,0]
	v_pk_mul_f32 v[26:27], v[26:27], v[94:95] op_sel_hi:[1,0]
	v_lshlrev_b32_e32 v170, 16, v158
	v_and_b32_e32 v171, 0xffff0000, v158
	v_lshlrev_b32_e32 v172, 16, v159
	v_and_b32_e32 v173, 0xffff0000, v159
	v_pk_mul_f32 v[24:25], v[112:113], v[24:25]
	v_pk_mul_f32 v[26:27], v[114:115], v[26:27]
	v_pk_mul_f32 v[24:25], v[24:25], v[170:171]
	v_pk_mul_f32 v[26:27], v[26:27], v[172:173]
	v_cvt_pk_bf16_f32 v24, v24, v25
	v_cvt_pk_bf16_f32 v25, v26, v27
	global_store_dwordx2 v[168:169], v[24:25], off offset:128
	v_pk_mul_f32 v[60:61], v[60:61], v[92:93] op_sel_hi:[1,0]
	v_pk_mul_f32 v[62:63], v[62:63], v[92:93] op_sel_hi:[1,0]
	v_lshlrev_b32_e32 v28, 16, v144
	v_and_b32_e32 v29, 0xffff0000, v144
	v_lshlrev_b32_e32 v30, 16, v145
	v_and_b32_e32 v31, 0xffff0000, v145
	v_pk_mul_f32 v[60:61], v[116:117], v[60:61]
	v_pk_mul_f32 v[62:63], v[118:119], v[62:63]
	v_pk_mul_f32 v[60:61], v[60:61], v[28:29]
	v_pk_mul_f32 v[62:63], v[62:63], v[30:31]
	v_cvt_pk_bf16_f32 v60, v60, v61
	v_cvt_pk_bf16_f32 v61, v62, v63
	global_store_dwordx2 v[166:167], v[60:61], off offset:160
	v_pk_mul_f32 v[20:21], v[20:21], v[94:95] op_sel_hi:[1,0]
	v_pk_mul_f32 v[22:23], v[22:23], v[94:95] op_sel_hi:[1,0]
	v_lshlrev_b32_e32 v170, 16, v160
	v_and_b32_e32 v171, 0xffff0000, v160
	v_lshlrev_b32_e32 v172, 16, v161
	v_and_b32_e32 v173, 0xffff0000, v161
	v_pk_mul_f32 v[20:21], v[116:117], v[20:21]
	v_pk_mul_f32 v[22:23], v[118:119], v[22:23]
	v_pk_mul_f32 v[20:21], v[20:21], v[170:171]
	v_pk_mul_f32 v[22:23], v[22:23], v[172:173]
	v_cvt_pk_bf16_f32 v20, v20, v21
	v_cvt_pk_bf16_f32 v21, v22, v23
	global_store_dwordx2 v[168:169], v[20:21], off offset:160
	v_pk_mul_f32 v[56:57], v[56:57], v[92:93] op_sel_hi:[1,0]
	v_pk_mul_f32 v[58:59], v[58:59], v[92:93] op_sel_hi:[1,0]
	v_lshlrev_b32_e32 v28, 16, v146
	v_and_b32_e32 v29, 0xffff0000, v146
	v_lshlrev_b32_e32 v30, 16, v147
	v_and_b32_e32 v31, 0xffff0000, v147
	v_pk_mul_f32 v[56:57], v[120:121], v[56:57]
	v_pk_mul_f32 v[58:59], v[122:123], v[58:59]
	v_pk_mul_f32 v[56:57], v[56:57], v[28:29]
	v_pk_mul_f32 v[58:59], v[58:59], v[30:31]
	v_cvt_pk_bf16_f32 v56, v56, v57
	v_cvt_pk_bf16_f32 v57, v58, v59
	global_store_dwordx2 v[166:167], v[56:57], off offset:192
	v_pk_mul_f32 v[16:17], v[16:17], v[94:95] op_sel_hi:[1,0]
	v_pk_mul_f32 v[18:19], v[18:19], v[94:95] op_sel_hi:[1,0]
	v_lshlrev_b32_e32 v170, 16, v162
	v_and_b32_e32 v171, 0xffff0000, v162
	v_lshlrev_b32_e32 v172, 16, v163
	v_and_b32_e32 v173, 0xffff0000, v163
	v_pk_mul_f32 v[16:17], v[120:121], v[16:17]
	v_pk_mul_f32 v[18:19], v[122:123], v[18:19]
	v_pk_mul_f32 v[16:17], v[16:17], v[170:171]
	v_pk_mul_f32 v[18:19], v[18:19], v[172:173]
	v_cvt_pk_bf16_f32 v16, v16, v17
	v_cvt_pk_bf16_f32 v17, v18, v19
	global_store_dwordx2 v[168:169], v[16:17], off offset:192
	v_pk_mul_f32 v[52:53], v[52:53], v[92:93] op_sel_hi:[1,0]
	v_pk_mul_f32 v[54:55], v[54:55], v[92:93] op_sel_hi:[1,0]
	v_lshlrev_b32_e32 v28, 16, v148
	v_and_b32_e32 v29, 0xffff0000, v148
	v_lshlrev_b32_e32 v30, 16, v149
	v_and_b32_e32 v31, 0xffff0000, v149
	v_pk_mul_f32 v[52:53], v[124:125], v[52:53]
	v_pk_mul_f32 v[54:55], v[126:127], v[54:55]
	v_pk_mul_f32 v[52:53], v[52:53], v[28:29]
	v_pk_mul_f32 v[54:55], v[54:55], v[30:31]
	v_cvt_pk_bf16_f32 v52, v52, v53
	v_cvt_pk_bf16_f32 v53, v54, v55
	global_store_dwordx2 v[166:167], v[52:53], off offset:224
	v_pk_mul_f32 v[12:13], v[12:13], v[94:95] op_sel_hi:[1,0]
	v_pk_mul_f32 v[14:15], v[14:15], v[94:95] op_sel_hi:[1,0]
	v_lshlrev_b32_e32 v170, 16, v164
	v_and_b32_e32 v171, 0xffff0000, v164
	v_lshlrev_b32_e32 v172, 16, v165
	v_and_b32_e32 v173, 0xffff0000, v165
	v_pk_mul_f32 v[12:13], v[124:125], v[12:13]
	v_pk_mul_f32 v[14:15], v[126:127], v[14:15]
	v_pk_mul_f32 v[12:13], v[12:13], v[170:171]
	v_pk_mul_f32 v[14:15], v[14:15], v[172:173]
	v_cvt_pk_bf16_f32 v12, v12, v13
	v_cvt_pk_bf16_f32 v13, v14, v15
	global_store_dwordx2 v[168:169], v[12:13], off offset:224
	v_readlane_b32 s17, v254, 44
	v_readlane_b32 s38, v254, 45
	v_readlane_b32 s39, v254, 46
	v_readlane_b32 s18, v254, 47
	v_readlane_b32 s40, v254, 48
	v_readlane_b32 s41, v254, 49
	v_readlane_b32 s43, v254, 50
	v_readlane_b32 s28, v254, 36
	v_readlane_b32 s30, v254, 37
	v_readlane_b32 s31, v254, 38
	v_readlane_b32 s88, v254, 39
	v_readlane_b32 s89, v254, 40
	v_readlane_b32 s29, v254, 41
	v_readlane_b32 s34, v254, 42
	v_readlane_b32 s35, v254, 43
	v_readlane_b32 s66, v254, 33
	v_readlane_b32 s84, v254, 34
	v_readlane_b32 s85, v254, 35
	v_readlane_b32 s78, v254, 32
	s_mov_b32 s27, 0
	s_movk_i32 s36, 0x3800
	s_mov_b64 s[14:15], 0x1800
	s_movk_i32 s16, 0x1000
	s_movk_i32 s37, 0x1c00
	s_mov_b64 s[96:97], 0x80
	s_movk_i32 s67, 0xe0
	s_movk_i32 s73, 0x60
	s_movk_i32 s74, 0x80
	s_movk_i32 s75, 0xa0
	s_movk_i32 s79, 0xc0
	s_mov_b64 s[92:93], 0x3000
	s_mov_b32 s42, 0x800000
	v_readlane_b32 s44, v255, 2
	v_readlane_b32 s2, v254, 51
	s_mov_b32 s98, 1
	s_mov_b32 s99, 0x0123467a
	s_branch .LBB0_565
